# weight-conversion loops of phases 1 and 5 rewritten by hand: dwordx4 tile loads in a 3-deep prefetch ring, double-buffered LDS transpose with one barrier per tile; phase-5 tiles assigned in contiguous
# baseline (speedup 1.0000x reference)
; DI unsigned pk2(float lo, float hi) { f32x2 v = {lo, hi}; bfv2 r = __builtin_convertvector(v, bfv2); return __builtin_bit_cast(unsigned, r); }
; DI void wconv(const float* __restrict__ src, int ld, int K, int col0, int ncols, bf16_t* __restrict__ dst, int dstld, int drow0, int mode, int bid, int nb) {
;     ...
;   if ((ncols & 63) == 0) {
;     const int ntn = ncols / 64, ntk = K / 64, nt = ntn * ntk;
;     for (int it = bid; it < nt; it += nb) {
;       const int tn = it % ntn, tk = it / ntn;
; #pragma unroll
;       for (int q = 0; q < 8; ++q) { int e = tid + 512 * q; int r = e >> 6, c = e & 63; t[r * 65 + c] = src[(size_t)(tk * 64 + r) * ld + col0 + tn * 64 + c]; }
;       __syncthreads();
;       { int n = tid >> 3, kk = (tid & 7) * 8; int cs = tn * 64 + n;
;         int drow = mode == 0 ? drow0 + cs : ((cs >> 7) * 256 + drow0 + (cs & 127));
;         u32x4 v; v.x = pk2(t[(kk) * 65 + n], t[(kk + 1) * 65 + n]); v.y = pk2(t[(kk + 2) * 65 + n], t[(kk + 3) * 65 + n]);
;         v.z = pk2(t[(kk + 4) * 65 + n], t[(kk + 5) * 65 + n]); v.w = pk2(t[(kk + 6) * 65 + n], t[(kk + 7) * 65 + n]);
;         *(u32x4*)(dst + (size_t)drow * dstld + tk * 64 + kk) = v; }
; DI void phase_pre(const P& p, int bid, int nb) {
;     ...
;   bf16_t* WIN = (bf16_t*)(p.ws + OFF_WIN);
; #pragma unroll 1
;   for (int job = 0; job < 7; ++job) {
;     int col0, ncols, drow0, mode = 0;
;     switch (job) { case 0: col0 = 0; ncols = 2048; drow0 = 0; break; case 1: col0 = 2080; ncols = 1024; drow0 = 2048; break;
;       case 2: col0 = 3104; ncols = 1024; drow0 = 3072; break;
;       case 3: col0 = 4128; ncols = 1024; drow0 = 4096; mode = 1; break;
;       case 4: col0 = 5152; ncols = 1024; drow0 = 4096 + 128; mode = 1; break;
;       case 5: col0 = 6176; ncols = 4096; drow0 = 6144; break; default: col0 = 2048; ncols = 32; drow0 = 10240; break; }
;     wconv(p.w_in, 10272, 2048, col0, ncols, WIN, 2048, drow0, mode, bid, nb);
.LBB0_72:
	s_or_b64 exec, exec, s[4:5]
	s_waitcnt vmcnt(0) lgkmcnt(0)
	v_and_b32_e32 v1, 0x3ff, v0
	v_lshrrev_b32_e32 v2, 4, v1
	v_and_b32_e32 v3, 15, v1
	v_lshrrev_b32_e32 v4, 3, v1
	v_and_b32_e32 v5, 7, v1
	v_mul_u32_u24_e32 v6, 0x41, v2
	v_lshl_add_u32 v6, v3, 2, v6
	v_lshlrev_b32_e32 v6, 2, v6
	v_mul_u32_u24_e32 v7, 0x208, v5
	v_add_u32_e32 v7, v7, v4
	v_lshlrev_b32_e32 v7, 2, v7
	s_mov_b32 s28, 0
	s_mov_b32 s3, 0
.Lwc1_job:
	s_cmp_eq_u32 s3, 0
	s_cbranch_scc1 .Lwc1_j0
	s_cmp_eq_u32 s3, 1
	s_cbranch_scc1 .Lwc1_j1
	s_cmp_eq_u32 s3, 2
	s_cbranch_scc1 .Lwc1_j2
	s_cmp_eq_u32 s3, 3
	s_cbranch_scc1 .Lwc1_j3
	s_cmp_eq_u32 s3, 4
	s_cbranch_scc1 .Lwc1_j4
	s_cmp_eq_u32 s3, 5
	s_cbranch_scc1 .Lwc1_j5
	s_cmp_eq_u32 s3, 6
	s_cbranch_scc1 .Lwc1_j6
	s_branch .Lwc1_alldone
.Lwc1_j0:
	v_readlane_b32 s10, v254, 20
	v_readlane_b32 s11, v254, 21
	s_mov_b32 s12, 0x2820
	s_mov_b32 s13, 32
	s_mov_b32 s14, 32
	s_mov_b32 s15, 0x0
	s_add_u32 s16, s84, 0x9200000
	s_addc_u32 s17, s85, 0
	s_mov_b32 s18, 0x800
	s_mov_b32 s19, 0
	s_mov_b32 s20, 0x0
	s_mov_b32 s21, 64
	s_branch .Lwc1_go
.Lwc1_j1:
	v_readlane_b32 s10, v254, 20
	v_readlane_b32 s11, v254, 21
	s_mov_b32 s12, 0x2820
	s_mov_b32 s13, 16
	s_mov_b32 s14, 32
	s_mov_b32 s15, 0x2080
	s_add_u32 s16, s84, 0x9200000
	s_addc_u32 s17, s85, 0
	s_mov_b32 s18, 0x800
	s_mov_b32 s19, 0
	s_mov_b32 s20, 0x800
	s_mov_b32 s21, 64
	s_branch .Lwc1_go
.Lwc1_j2:
	v_readlane_b32 s10, v254, 20
	v_readlane_b32 s11, v254, 21
	s_mov_b32 s12, 0x2820
	s_mov_b32 s13, 16
	s_mov_b32 s14, 32
	s_mov_b32 s15, 0x3080
	s_add_u32 s16, s84, 0x9200000
	s_addc_u32 s17, s85, 0
	s_mov_b32 s18, 0x800
	s_mov_b32 s19, 0
	s_mov_b32 s20, 0xc00
	s_mov_b32 s21, 64
	s_branch .Lwc1_go
.Lwc1_j3:
	v_readlane_b32 s10, v254, 20
	v_readlane_b32 s11, v254, 21
	s_mov_b32 s12, 0x2820
	s_mov_b32 s13, 16
	s_mov_b32 s14, 32
	s_mov_b32 s15, 0x4080
	s_add_u32 s16, s84, 0x9200000
	s_addc_u32 s17, s85, 0
	s_mov_b32 s18, 0x800
	s_mov_b32 s19, 1
	s_mov_b32 s20, 0x1000
	s_mov_b32 s21, 64
	s_branch .Lwc1_go
.Lwc1_j4:
	v_readlane_b32 s10, v254, 20
	v_readlane_b32 s11, v254, 21
	s_mov_b32 s12, 0x2820
	s_mov_b32 s13, 16
	s_mov_b32 s14, 32
	s_mov_b32 s15, 0x5080
	s_add_u32 s16, s84, 0x9200000
	s_addc_u32 s17, s85, 0
	s_mov_b32 s18, 0x800
	s_mov_b32 s19, 1
	s_mov_b32 s20, 0x1080
	s_mov_b32 s21, 64
	s_branch .Lwc1_go
.Lwc1_j5:
	v_readlane_b32 s10, v254, 20
	v_readlane_b32 s11, v254, 21
	s_mov_b32 s12, 0x2820
	s_mov_b32 s13, 64
	s_mov_b32 s14, 32
	s_mov_b32 s15, 0x6080
	s_add_u32 s16, s84, 0x9200000
	s_addc_u32 s17, s85, 0
	s_mov_b32 s18, 0x800
	s_mov_b32 s19, 0
	s_mov_b32 s20, 0x1800
	s_mov_b32 s21, 64
	s_branch .Lwc1_go
.Lwc1_j6:
	v_readlane_b32 s10, v254, 20
	v_readlane_b32 s11, v254, 21
	s_mov_b32 s12, 0x2820
	s_mov_b32 s13, 1
	s_mov_b32 s14, 32
	s_mov_b32 s15, 0x2000
	s_add_u32 s16, s84, 0x9200000
	s_addc_u32 s17, s85, 0
	s_mov_b32 s18, 0x800
	s_mov_b32 s19, 0
	s_mov_b32 s20, 0x2800
	s_mov_b32 s21, 32
	s_branch .Lwc1_go
.Lwc1_go:
	s_nop 1
	s_add_u32 s10, s10, s15
	s_addc_u32 s11, s11, 0
	v_mul_lo_u32 v8, v2, s12
	v_lshlrev_b32_e32 v8, 2, v8
	v_lshl_add_u32 v8, v3, 4, v8
	s_lshl_b32 s29, s12, 7
	v_add_u32_e32 v13, s29, v8
	v_mul_lo_u32 v9, v4, s18
	v_lshlrev_b32_e32 v9, 1, v9
	v_lshl_add_u32 v9, v5, 4, v9
	v_cmp_gt_u32_e32 vcc, s21, v4
	s_nop 1
	v_cndmask_b32_e64 v12, 0, 1, vcc
	s_mul_i32 s14, s14, s13
	s_mov_b32 s4, 0
	s_mov_b32 s15, s2
.Lwc1_cnt:
	s_cmp_ge_u32 s15, s14
	s_cbranch_scc1 .Lwc1_cntd
	s_add_u32 s4, s4, 1
	s_add_u32 s15, s15, s88
	s_branch .Lwc1_cnt
.Lwc1_cntd:
	s_cmp_eq_u32 s4, 0
	s_cbranch_scc1 .Lwc1_jobdone
	s_mov_b32 s7, 0
	s_mov_b32 s6, s2
.Lwc1_dma:
	s_cmp_lt_u32 s6, s13
	s_cbranch_scc1 .Lwc1_dmda
	s_sub_u32 s6, s6, s13
	s_add_u32 s7, s7, 1
	s_branch .Lwc1_dma
.Lwc1_dmda:
	s_mov_b32 s22, 0
	s_mov_b32 s23, s88
.Lwc1_dmb:
	s_cmp_lt_u32 s23, s13
	s_cbranch_scc1 .Lwc1_dmdb
	s_sub_u32 s23, s23, s13
	s_add_u32 s22, s22, 1
	s_branch .Lwc1_dmb
.Lwc1_dmdb:
.Lwc1_coords:
	s_mov_b32 s8, s6
	s_mov_b32 s9, s7
	s_mov_b32 s5, 0
	s_lshl_b32 s21, s12, 8
	s_mul_i32 s21, s7, s21
	s_lshl_b32 s29, s6, 8
	s_add_u32 s21, s21, s29
	s_add_u32 s24, s10, s21
	s_addc_u32 s25, s11, 0
	global_load_dwordx4 v[16:19], v8, s[24:25]
	global_load_dwordx4 v[20:23], v13, s[24:25]
	s_add_u32 s6, s6, s23
	s_add_u32 s7, s7, s22
	s_cmp_ge_u32 s6, s13
	s_cselect_b32 s21, s13, 0
	s_cselect_b32 s15, 1, 0
	s_sub_u32 s6, s6, s21
	s_add_u32 s7, s7, s15
	s_cmp_lt_u32 s4, 2
	s_cbranch_scc1 .Lwc1_b0
	s_lshl_b32 s21, s12, 8
	s_mul_i32 s21, s7, s21
	s_lshl_b32 s29, s6, 8
	s_add_u32 s21, s21, s29
	s_add_u32 s24, s10, s21
	s_addc_u32 s25, s11, 0
	global_load_dwordx4 v[24:27], v8, s[24:25]
	global_load_dwordx4 v[28:31], v13, s[24:25]
	s_add_u32 s6, s6, s23
	s_add_u32 s7, s7, s22
	s_cmp_ge_u32 s6, s13
	s_cselect_b32 s21, s13, 0
	s_cselect_b32 s15, 1, 0
	s_sub_u32 s6, s6, s21
	s_add_u32 s7, s7, s15
.Lwc1_b0:
	s_add_u32 s15, s5, 2
	s_cmp_lt_u32 s15, s4
	s_cbranch_scc0 .Lwc1_w0_0
	s_lshl_b32 s21, s12, 8
	s_mul_i32 s21, s7, s21
	s_lshl_b32 s29, s6, 8
	s_add_u32 s21, s21, s29
	s_add_u32 s24, s10, s21
	s_addc_u32 s25, s11, 0
	global_load_dwordx4 v[32:35], v8, s[24:25]
	global_load_dwordx4 v[36:39], v13, s[24:25]
	s_add_u32 s6, s6, s23
	s_add_u32 s7, s7, s22
	s_cmp_ge_u32 s6, s13
	s_cselect_b32 s21, s13, 0
	s_cselect_b32 s15, 1, 0
	s_sub_u32 s6, s6, s21
	s_add_u32 s7, s7, s15
	s_cmp_lt_u32 s5, 2
	s_cbranch_scc1 .Lwc1_w4_0
	s_waitcnt vmcnt(6)
	s_branch .Lwc1_wd_0
.Lwc1_w4_0:
	s_waitcnt vmcnt(4)
	s_branch .Lwc1_wd_0

; DI unsigned pk2(float lo, float hi) { f32x2 v = {lo, hi}; bfv2 r = __builtin_convertvector(v, bfv2); return __builtin_bit_cast(unsigned, r); }
; DI void wconv(const float* __restrict__ src, int ld, int K, int col0, int ncols, bf16_t* __restrict__ dst, int dstld, int drow0, int mode, int bid, int nb) {
;     ...
;       for (int q = 0; q < 8; ++q) { int e = tid + 512 * q; int r = e >> 6, c = e & 63; t[r * 65 + c] = src[(size_t)(tk * 64 + r) * ld + col0 + tn * 64 + c]; }
;       __syncthreads();
;       { int n = tid >> 3, kk = (tid & 7) * 8; int cs = tn * 64 + n;
;         int drow = mode == 0 ? drow0 + cs : ((cs >> 7) * 256 + drow0 + (cs & 127));
;         u32x4 v; v.x = pk2(t[(kk) * 65 + n], t[(kk + 1) * 65 + n]); v.y = pk2(t[(kk + 2) * 65 + n], t[(kk + 3) * 65 + n]);
;         v.z = pk2(t[(kk + 4) * 65 + n], t[(kk + 5) * 65 + n]); v.w = pk2(t[(kk + 6) * 65 + n], t[(kk + 7) * 65 + n]);
;         *(u32x4*)(dst + (size_t)drow * dstld + tk * 64 + kk) = v; }
;       __syncthreads();
.Lwc1_wd_0:
	v_add_u32_e32 v10, s28, v6
	v_add_u32_e32 v11, s28, v7
	ds_write_b32 v10, v16
	ds_write_b32 v10, v17 offset:4
	ds_write_b32 v10, v18 offset:8
	ds_write_b32 v10, v19 offset:12
	ds_write_b32 v10, v20 offset:8320
	ds_write_b32 v10, v21 offset:8324
	ds_write_b32 v10, v22 offset:8328
	ds_write_b32 v10, v23 offset:8332
	s_lshl_b32 s15, s8, 6
	s_lshr_b32 s21, s8, 1
	s_lshl_b32 s21, s21, 8
	s_and_b32 s29, s8, 1
	s_lshl_b32 s29, s29, 6
	s_add_u32 s21, s21, s29
	s_cmp_eq_u32 s19, 0
	s_cselect_b32 s15, s15, s21
	s_add_u32 s15, s15, s20
	s_mul_i32 s15, s15, s18
	s_lshl_b32 s21, s9, 6
	s_add_u32 s15, s15, s21
	s_lshl_b32 s15, s15, 1
	s_add_u32 s26, s16, s15
	s_addc_u32 s27, s17, 0
	s_add_u32 s8, s8, s23
	s_add_u32 s9, s9, s22
	s_cmp_ge_u32 s8, s13
	s_cselect_b32 s21, s13, 0
	s_cselect_b32 s15, 1, 0
	s_sub_u32 s8, s8, s21
	s_add_u32 s9, s9, s15
	s_xor_b32 s28, s28, 0x4100
	s_waitcnt lgkmcnt(0)
	s_barrier
	ds_read_b32 v40, v11
	ds_read_b32 v41, v11 offset:260
	ds_read_b32 v42, v11 offset:520
	ds_read_b32 v43, v11 offset:780
	ds_read_b32 v44, v11 offset:1040
	ds_read_b32 v45, v11 offset:1300
	ds_read_b32 v46, v11 offset:1560
	ds_read_b32 v47, v11 offset:1820
	s_waitcnt lgkmcnt(0)
	v_cvt_pk_bf16_f32 v48, v40, v41
	v_cvt_pk_bf16_f32 v49, v42, v43
	v_cvt_pk_bf16_f32 v50, v44, v45
	v_cvt_pk_bf16_f32 v51, v46, v47
	v_cmp_ne_u32_e32 vcc, 0, v12
	s_and_b64 exec, exec, vcc
	global_store_dwordx4 v9, v[48:51], s[26:27]
	s_mov_b64 exec, -1
	s_add_u32 s5, s5, 1
	s_cmp_ge_u32 s5, s4
	s_cbranch_scc1 .Lwc1_jobdone
.Lwc1_b1:
	s_add_u32 s15, s5, 2
	s_cmp_lt_u32 s15, s4
	s_cbranch_scc0 .Lwc1_w0_1
	s_lshl_b32 s21, s12, 8
	s_mul_i32 s21, s7, s21
	s_lshl_b32 s29, s6, 8
	s_add_u32 s21, s21, s29
	s_add_u32 s24, s10, s21
	s_addc_u32 s25, s11, 0
	global_load_dwordx4 v[16:19], v8, s[24:25]
	global_load_dwordx4 v[20:23], v13, s[24:25]
	s_add_u32 s6, s6, s23
	s_add_u32 s7, s7, s22
	s_cmp_ge_u32 s6, s13
	s_cselect_b32 s21, s13, 0
	s_cselect_b32 s15, 1, 0
	s_sub_u32 s6, s6, s21
	s_add_u32 s7, s7, s15
	s_cmp_lt_u32 s5, 2
	s_cbranch_scc1 .Lwc1_w4_1
	s_waitcnt vmcnt(6)
	s_branch .Lwc1_wd_1

; DI unsigned pk2(float lo, float hi) { f32x2 v = {lo, hi}; bfv2 r = __builtin_convertvector(v, bfv2); return __builtin_bit_cast(unsigned, r); }
; DI void wconv(const float* __restrict__ src, int ld, int K, int col0, int ncols, bf16_t* __restrict__ dst, int dstld, int drow0, int mode, int bid, int nb) {
;     ...
;       for (int q = 0; q < 8; ++q) { int e = tid + 512 * q; int r = e >> 6, c = e & 63; t[r * 65 + c] = src[(size_t)(tk * 64 + r) * ld + col0 + tn * 64 + c]; }
;       __syncthreads();
;       { int n = tid >> 3, kk = (tid & 7) * 8; int cs = tn * 64 + n;
;         int drow = mode == 0 ? drow0 + cs : ((cs >> 7) * 256 + drow0 + (cs & 127));
;         u32x4 v; v.x = pk2(t[(kk) * 65 + n], t[(kk + 1) * 65 + n]); v.y = pk2(t[(kk + 2) * 65 + n], t[(kk + 3) * 65 + n]);
;         v.z = pk2(t[(kk + 4) * 65 + n], t[(kk + 5) * 65 + n]); v.w = pk2(t[(kk + 6) * 65 + n], t[(kk + 7) * 65 + n]);
;         *(u32x4*)(dst + (size_t)drow * dstld + tk * 64 + kk) = v; }
;       __syncthreads();
.Lwc1_wd_1:
	v_add_u32_e32 v10, s28, v6
	v_add_u32_e32 v11, s28, v7
	ds_write_b32 v10, v24
	ds_write_b32 v10, v25 offset:4
	ds_write_b32 v10, v26 offset:8
	ds_write_b32 v10, v27 offset:12
	ds_write_b32 v10, v28 offset:8320
	ds_write_b32 v10, v29 offset:8324
	ds_write_b32 v10, v30 offset:8328
	ds_write_b32 v10, v31 offset:8332
	s_lshl_b32 s15, s8, 6
	s_lshr_b32 s21, s8, 1
	s_lshl_b32 s21, s21, 8
	s_and_b32 s29, s8, 1
	s_lshl_b32 s29, s29, 6
	s_add_u32 s21, s21, s29
	s_cmp_eq_u32 s19, 0
	s_cselect_b32 s15, s15, s21
	s_add_u32 s15, s15, s20
	s_mul_i32 s15, s15, s18
	s_lshl_b32 s21, s9, 6
	s_add_u32 s15, s15, s21
	s_lshl_b32 s15, s15, 1
	s_add_u32 s26, s16, s15
	s_addc_u32 s27, s17, 0
	s_add_u32 s8, s8, s23
	s_add_u32 s9, s9, s22
	s_cmp_ge_u32 s8, s13
	s_cselect_b32 s21, s13, 0
	s_cselect_b32 s15, 1, 0
	s_sub_u32 s8, s8, s21
	s_add_u32 s9, s9, s15
	s_xor_b32 s28, s28, 0x4100
	s_waitcnt lgkmcnt(0)
	s_barrier
	ds_read_b32 v40, v11
	ds_read_b32 v41, v11 offset:260
	ds_read_b32 v42, v11 offset:520
	ds_read_b32 v43, v11 offset:780
	ds_read_b32 v44, v11 offset:1040
	ds_read_b32 v45, v11 offset:1300
	ds_read_b32 v46, v11 offset:1560
	ds_read_b32 v47, v11 offset:1820
	s_waitcnt lgkmcnt(0)
	v_cvt_pk_bf16_f32 v48, v40, v41
	v_cvt_pk_bf16_f32 v49, v42, v43
	v_cvt_pk_bf16_f32 v50, v44, v45
	v_cvt_pk_bf16_f32 v51, v46, v47
	v_cmp_ne_u32_e32 vcc, 0, v12
	s_and_b64 exec, exec, vcc
	global_store_dwordx4 v9, v[48:51], s[26:27]
	s_mov_b64 exec, -1
	s_add_u32 s5, s5, 1
	s_cmp_ge_u32 s5, s4
	s_cbranch_scc1 .Lwc1_jobdone
.Lwc1_b2:
	s_add_u32 s15, s5, 2
	s_cmp_lt_u32 s15, s4
	s_cbranch_scc0 .Lwc1_w0_2
	s_lshl_b32 s21, s12, 8
	s_mul_i32 s21, s7, s21
	s_lshl_b32 s29, s6, 8
	s_add_u32 s21, s21, s29
	s_add_u32 s24, s10, s21
	s_addc_u32 s25, s11, 0
	global_load_dwordx4 v[24:27], v8, s[24:25]
	global_load_dwordx4 v[28:31], v13, s[24:25]
	s_add_u32 s6, s6, s23
	s_add_u32 s7, s7, s22
	s_cmp_ge_u32 s6, s13
	s_cselect_b32 s21, s13, 0
	s_cselect_b32 s15, 1, 0
	s_sub_u32 s6, s6, s21
	s_add_u32 s7, s7, s15
	s_cmp_lt_u32 s5, 2
	s_cbranch_scc1 .Lwc1_w4_2
	s_waitcnt vmcnt(6)
	s_branch .Lwc1_wd_2

; DI unsigned pk2(float lo, float hi) { f32x2 v = {lo, hi}; bfv2 r = __builtin_convertvector(v, bfv2); return __builtin_bit_cast(unsigned, r); }
; DI void wconv(const float* __restrict__ src, int ld, int K, int col0, int ncols, bf16_t* __restrict__ dst, int dstld, int drow0, int mode, int bid, int nb) {
;     ...
;       for (int q = 0; q < 8; ++q) { int e = tid + 512 * q; int r = e >> 6, c = e & 63; t[r * 65 + c] = src[(size_t)(tk * 64 + r) * ld + col0 + tn * 64 + c]; }
;       __syncthreads();
;       { int n = tid >> 3, kk = (tid & 7) * 8; int cs = tn * 64 + n;
;         int drow = mode == 0 ? drow0 + cs : ((cs >> 7) * 256 + drow0 + (cs & 127));
;         u32x4 v; v.x = pk2(t[(kk) * 65 + n], t[(kk + 1) * 65 + n]); v.y = pk2(t[(kk + 2) * 65 + n], t[(kk + 3) * 65 + n]);
;         v.z = pk2(t[(kk + 4) * 65 + n], t[(kk + 5) * 65 + n]); v.w = pk2(t[(kk + 6) * 65 + n], t[(kk + 7) * 65 + n]);
;         *(u32x4*)(dst + (size_t)drow * dstld + tk * 64 + kk) = v; }
;       __syncthreads();
;     }
;     return;
.Lwc1_wd_2:
	v_add_u32_e32 v10, s28, v6
	v_add_u32_e32 v11, s28, v7
	ds_write_b32 v10, v32
	ds_write_b32 v10, v33 offset:4
	ds_write_b32 v10, v34 offset:8
	ds_write_b32 v10, v35 offset:12
	ds_write_b32 v10, v36 offset:8320
	ds_write_b32 v10, v37 offset:8324
	ds_write_b32 v10, v38 offset:8328
	ds_write_b32 v10, v39 offset:8332
	s_lshl_b32 s15, s8, 6
	s_lshr_b32 s21, s8, 1
	s_lshl_b32 s21, s21, 8
	s_and_b32 s29, s8, 1
	s_lshl_b32 s29, s29, 6
	s_add_u32 s21, s21, s29
	s_cmp_eq_u32 s19, 0
	s_cselect_b32 s15, s15, s21
	s_add_u32 s15, s15, s20
	s_mul_i32 s15, s15, s18
	s_lshl_b32 s21, s9, 6
	s_add_u32 s15, s15, s21
	s_lshl_b32 s15, s15, 1
	s_add_u32 s26, s16, s15
	s_addc_u32 s27, s17, 0
	s_add_u32 s8, s8, s23
	s_add_u32 s9, s9, s22
	s_cmp_ge_u32 s8, s13
	s_cselect_b32 s21, s13, 0
	s_cselect_b32 s15, 1, 0
	s_sub_u32 s8, s8, s21
	s_add_u32 s9, s9, s15
	s_xor_b32 s28, s28, 0x4100
	s_waitcnt lgkmcnt(0)
	s_barrier
	ds_read_b32 v40, v11
	ds_read_b32 v41, v11 offset:260
	ds_read_b32 v42, v11 offset:520
	ds_read_b32 v43, v11 offset:780
	ds_read_b32 v44, v11 offset:1040
	ds_read_b32 v45, v11 offset:1300
	ds_read_b32 v46, v11 offset:1560
	ds_read_b32 v47, v11 offset:1820
	s_waitcnt lgkmcnt(0)
	v_cvt_pk_bf16_f32 v48, v40, v41
	v_cvt_pk_bf16_f32 v49, v42, v43
	v_cvt_pk_bf16_f32 v50, v44, v45
	v_cvt_pk_bf16_f32 v51, v46, v47
	v_cmp_ne_u32_e32 vcc, 0, v12
	s_and_b64 exec, exec, vcc
	global_store_dwordx4 v9, v[48:51], s[26:27]
	s_mov_b64 exec, -1
	s_add_u32 s5, s5, 1
	s_cmp_ge_u32 s5, s4
	s_cbranch_scc1 .Lwc1_jobdone
	s_branch .Lwc1_b0
.Lwc1_jobdone:
	s_add_u32 s3, s3, 1
	s_branch .Lwc1_job
.Lwc1_alldone:
	v_and_b32_e32 v2, 0x3ff, v0

; DI unsigned pk2(float lo, float hi) { f32x2 v = {lo, hi}; bfv2 r = __builtin_convertvector(v, bfv2); return __builtin_bit_cast(unsigned, r); }
; DI void wconv(const float* __restrict__ src, int ld, int K, int col0, int ncols, bf16_t* __restrict__ dst, int dstld, int drow0, int mode, int bid, int nb) {
;     ...
;   if ((ncols & 63) == 0) {
;     const int ntn = ncols / 64, ntk = K / 64, nt = ntn * ntk;
;     for (int it = bid; it < nt; it += nb) {
;       const int tn = it % ntn, tk = it / ntn;
; #pragma unroll
;       for (int q = 0; q < 8; ++q) { int e = tid + 512 * q; int r = e >> 6, c = e & 63; t[r * 65 + c] = src[(size_t)(tk * 64 + r) * ld + col0 + tn * 64 + c]; }
;       __syncthreads();
;       { int n = tid >> 3, kk = (tid & 7) * 8; int cs = tn * 64 + n;
;         int drow = mode == 0 ? drow0 + cs : ((cs >> 7) * 256 + drow0 + (cs & 127));
;         u32x4 v; v.x = pk2(t[(kk) * 65 + n], t[(kk + 1) * 65 + n]); v.y = pk2(t[(kk + 2) * 65 + n], t[(kk + 3) * 65 + n]);
;         v.z = pk2(t[(kk + 4) * 65 + n], t[(kk + 5) * 65 + n]); v.w = pk2(t[(kk + 6) * 65 + n], t[(kk + 7) * 65 + n]);
;         *(u32x4*)(dst + (size_t)drow * dstld + tk * 64 + kk) = v; }
; DI void phase_global_b(const P& p, int bid, int nb) {
;     ...
;   for (int job = 0; job < 6; ++job) {
;     const float* src; int ld, K, ncols, dstld, drow0, mode; bf16_t* dst;
;     switch (job) {
;       case 0: src = p.p_gla; ld = 2048; K = 1024; ncols = 2048; dst = W2 + W2_PM / 2; dstld = 2048; drow0 = 0; mode = 0; break;
;       case 1: src = p.p_hy; ld = 2048; K = 1024; ncols = 2048; dst = W2 + W2_PM / 2 + 1024; dstld = 2048; drow0 = 0; mode = 0; break;
;       case 2: src = p.w_out; ld = 2048; K = 2048; ncols = 2048; dst = W2 + W2_WOUT / 2; dstld = 2048; drow0 = 0; mode = 0; break;
;       case 3: src = p.ffn_gate; ld = 5632; K = 2048; ncols = 5632; dst = W2 + W2_WGU / 2; dstld = 2048; drow0 = 0; mode = 1; break;
;       case 4: src = p.ffn_up; ld = 5632; K = 2048; ncols = 5632; dst = W2 + W2_WGU / 2; dstld = 2048; drow0 = 128; mode = 1; break;
;       default: src = p.ffn_down; ld = 2048; K = 5632; ncols = 2048; dst = W2 + W2_WD / 2; dstld = 5632; drow0 = 0; mode = 0; break; }
;     wconv(src, ld, K, 0, ncols, dst, dstld, drow0, mode, bid, nb);
.LBB0_470:
	s_waitcnt vmcnt(0) lgkmcnt(0)
	v_and_b32_e32 v1, 0x3ff, v0
	v_lshrrev_b32_e32 v2, 4, v1
	v_and_b32_e32 v3, 15, v1
	v_lshrrev_b32_e32 v4, 3, v1
	v_and_b32_e32 v5, 7, v1
	v_mul_u32_u24_e32 v6, 0x41, v2
	v_lshl_add_u32 v6, v3, 2, v6
	v_lshlrev_b32_e32 v6, 2, v6
	v_mul_u32_u24_e32 v7, 0x208, v5
	v_add_u32_e32 v7, v7, v4
	v_lshlrev_b32_e32 v7, 2, v7
	s_mov_b32 s28, 0
	s_mov_b32 s3, 0
	s_and_b32 s38, s2, 15
	s_lshr_b32 s39, s2, 4
	s_mul_i32 s40, s39, 0xc8
	s_mul_i32 s41, s38, 20
	s_add_u32 s40, s40, s41
	s_sub_u32 s41, s38, 1
	s_mul_i32 s41, s41, s38
	s_lshr_b32 s41, s41, 1
	s_sub_u32 s40, s40, s41
	s_sub_u32 s41, 20, s38
	s_add_u32 s41, s40, s41
.Lwc5_job:
	s_cmp_eq_u32 s3, 0
	s_cbranch_scc1 .Lwc5_j0
	s_cmp_eq_u32 s3, 1
	s_cbranch_scc1 .Lwc5_j1
	s_cmp_eq_u32 s3, 2
	s_cbranch_scc1 .Lwc5_j2
	s_cmp_eq_u32 s3, 3
	s_cbranch_scc1 .Lwc5_j3
	s_cmp_eq_u32 s3, 4
	s_cbranch_scc1 .Lwc5_j4
	s_cmp_eq_u32 s3, 5
	s_cbranch_scc1 .Lwc5_j5
	s_branch .Lwc5_alldone
.Lwc5_j0:
	v_readlane_b32 s10, v254, 34
	v_readlane_b32 s11, v254, 35
	s_mov_b32 s12, 0x800
	s_mov_b32 s13, 32
	s_mov_b32 s14, 16
	s_mov_b32 s15, 0x0
	s_add_u32 s16, s84, 0x13b00000
	s_addc_u32 s17, s85, 0
	s_mov_b32 s18, 0x800
	s_mov_b32 s19, 0
	s_mov_b32 s20, 0x0
	s_mov_b32 s21, 64
	s_branch .Lwc5_go
.Lwc5_j1:
	v_readlane_b32 s10, v254, 36
	v_readlane_b32 s11, v254, 37
	s_mov_b32 s12, 0x800
	s_mov_b32 s13, 32
	s_mov_b32 s14, 16
	s_mov_b32 s15, 0x0
	s_add_u32 s16, s84, 0x13b00800
	s_addc_u32 s17, s85, 0
	s_mov_b32 s18, 0x800
	s_mov_b32 s19, 0
	s_mov_b32 s20, 0x0
	s_mov_b32 s21, 64
	s_branch .Lwc5_go
.Lwc5_j2:
	v_readlane_b32 s10, v254, 38
	v_readlane_b32 s11, v254, 39
	s_mov_b32 s12, 0x800
	s_mov_b32 s13, 32
	s_mov_b32 s14, 32
	s_mov_b32 s15, 0x0
	s_add_u32 s16, s84, 0x14300000
	s_addc_u32 s17, s85, 0
	s_mov_b32 s18, 0x800
	s_mov_b32 s19, 0
	s_mov_b32 s20, 0x0
	s_mov_b32 s21, 64
	s_branch .Lwc5_go
.Lwc5_j3:
	v_readlane_b32 s10, v254, 40
	v_readlane_b32 s11, v254, 41
	s_mov_b32 s12, 0x1600
	s_mov_b32 s13, 88
	s_mov_b32 s14, 32
	s_mov_b32 s15, 0x0
	s_add_u32 s16, s84, 0x14b00000
	s_addc_u32 s17, s85, 0
	s_mov_b32 s18, 0x800
	s_mov_b32 s19, 1
	s_mov_b32 s20, 0x0
	s_mov_b32 s21, 64
	s_branch .Lwc5_go
.Lwc5_j4:
	v_readlane_b32 s10, v254, 42
	v_readlane_b32 s11, v254, 43
	s_mov_b32 s12, 0x1600
	s_mov_b32 s13, 88
	s_mov_b32 s14, 32
	s_mov_b32 s15, 0x0
	s_add_u32 s16, s84, 0x14b00000
	s_addc_u32 s17, s85, 0
	s_mov_b32 s18, 0x800
	s_mov_b32 s19, 1
	s_mov_b32 s20, 0x80
	s_mov_b32 s21, 64
	s_branch .Lwc5_go
.Lwc5_j5:
	v_readlane_b32 s10, v254, 44
	v_readlane_b32 s11, v254, 45
	s_mov_b32 s12, 0x800
	s_mov_b32 s13, 32
	s_mov_b32 s14, 88
	s_mov_b32 s15, 0x0
	s_add_u32 s16, s84, 0x17700000
	s_addc_u32 s17, s85, 0
	s_mov_b32 s18, 0x1600
	s_mov_b32 s19, 0
	s_mov_b32 s20, 0x0
	s_mov_b32 s21, 64
	s_branch .Lwc5_go
.Lwc5_go:
	s_nop 1
	s_add_u32 s10, s10, s15
	s_addc_u32 s11, s11, 0
	v_mul_lo_u32 v8, v2, s12
	v_lshlrev_b32_e32 v8, 2, v8
	v_lshl_add_u32 v8, v3, 4, v8
	s_lshl_b32 s29, s12, 7
	v_add_u32_e32 v13, s29, v8
	v_mul_lo_u32 v9, v4, s18
	v_lshlrev_b32_e32 v9, 1, v9
	v_lshl_add_u32 v9, v5, 4, v9
	v_cmp_gt_u32_e32 vcc, s21, v4
	s_nop 1
	v_cndmask_b32_e64 v12, 0, 1, vcc
	s_mul_i32 s14, s14, s13
	s_cmp_eq_u32 s88, 0x100
	s_cbranch_scc0 .Lwc5_strided
	s_mul_i32 s42, s14, s40
	s_lshr_b32 s42, s42, 7
	s_mul_hi_u32 s42, s42, 0x51eb851f
	s_lshr_b32 s42, s42, 3
	s_mul_i32 s43, s14, s41
	s_lshr_b32 s43, s43, 7
	s_mul_hi_u32 s43, s43, 0x51eb851f
	s_lshr_b32 s43, s43, 3
	s_sub_u32 s4, s43, s42
	s_cmp_eq_u32 s4, 0
	s_cbranch_scc1 .Lwc5_jobdone
	s_mov_b32 s7, 0
	s_mov_b32 s6, s42

; DI void wconv(const float* __restrict__ src, int ld, int K, int col0, int ncols, bf16_t* __restrict__ dst, int dstld, int drow0, int mode, int bid, int nb) {
;     ...
;     for (int it = bid; it < nt; it += nb) {
;       const int tn = it % ntn, tk = it / ntn;
.Lwc5_dmwd:
	s_mov_b32 s22, 0
	s_mov_b32 s23, 1
	s_branch .Lwc5_coords
.Lwc5_strided:
	s_mov_b32 s4, 0
	s_mov_b32 s15, s2

; #define RUN_PH(k, call) do { if (ph_lo <= (k) && (k) < ph_hi) { if ((k) > ph_lo) { if ((k) == 1) grid.sync(); else grid_barrier(gcnt, (unsigned)((k) - 1) * (unsigned)nb); } call; } } while (0)
; __global__ void __launch_bounds__(NTHREADS) hybrid_layer_kernel(P p, int ph_lo, int ph_hi) {
;     ...
;   RUN_PH(6, phase_mergeprep(p, bid, nb));
.Lwc5_alldone:
.LBB0_497:
	s_cmp_gt_i32 s86, 6
	s_cselect_b64 s[8:9], -1, 0
	s_cmp_lt_i32 s87, 7
	s_cselect_b64 s[4:5], -1, 0
	s_or_b64 s[4:5], s[8:9], s[4:5]
	s_and_b64 vcc, exec, s[4:5]
	s_cbranch_vccnz .LBB0_526
	s_andn2_b64 vcc, exec, s[0:1]
	s_cbranch_vccnz .LBB0_500
	s_waitcnt vmcnt(0)
	v_and_b32_e32 v29, 0x3ff, v0
	s_cbranch_execz .LBB0_501
	s_branch .LBB0_508
